# no store drain (vmcnt(0)) at the end of the P2 and P6 GEMM epilogues: vmcnt retires in issue order, so the K-loop's counted waits stay correct with older stores outstanding
# baseline (speedup 1.0000x reference)
.LBB0_512:
.LBB0_513:
	s_nop 0
	s_andn2_b64 vcc, exec, s[12:13]
	s_mov_b64 s[12:13], -1
	v_readlane_b32 s84, v254, 53
	s_cbranch_vccnz .LBB0_411
	v_readlane_b32 s12, v255, 6
	v_readlane_b32 s13, v255, 7
	s_and_b64 vcc, exec, s[12:13]
	s_cbranch_vccnz .LBB0_410
	s_barrier
	s_branch .LBB0_410

.LBB0_1292:
	s_nop 0
	s_andn2_b64 vcc, exec, s[22:23]
	s_mov_b64 s[22:23], -1
	s_cbranch_vccnz .LBB0_1272
	v_readlane_b32 s22, v255, 6
	v_readlane_b32 s23, v255, 7
	s_and_b64 vcc, exec, s[22:23]
	s_cbranch_vccnz .LBB0_1271
	s_barrier
	s_branch .LBB0_1271
